# C1: DFT combine pass: second item's four loads issued before the first consumer wait (hipcc had hoisted it above them); rest of the kernel +64 bytes; on top of K1+R1+S1+Z1
# baseline (speedup 1.0000x reference)
; __device__ __forceinline__ u32x4 pack8(const f32x4& a, const f32x4& b) { u32x4 w; w.x = cvt_pk_bf16(a[0], a[1]); w.y = cvt_pk_bf16(a[2], a[3]); w.z = cvt_pk_bf16(b[0], b[1]); w.w = cvt_pk_bf16(b[2], b[3]); return w; }
; __device__ __forceinline__ void dft_combine(const Args& a, int gt, int NT, int lane, int gw, int NGW) {
;     ...
;     for (int idx0 = gt; idx0 < 1024 * 512; idx0 += 2 * NT) {
;         typedef _Float16 h8 __attribute__((ext_vector_type(8))); typedef float f8 __attribute__((ext_vector_type(8)));
;         f32x4 v[2][8]; int kk[2], bb[2], cc8[2]; bool okk[2];
; #pragma unroll
;         for (int u = 0; u < 2; ++u) {
;             const int idx = idx0 + u * NT; okk[u] = idx < 1024 * 512; const int id = okk[u] ? idx : idx0;
;             kk[u] = id >> 9; const int cc = id & 511; bb[u] = cc >> 6; cc8[u] = (cc & 63) * 8;
;             const _Float16* p = SL + (size_t)kk[u] * 4096 + bb[u] * 512 + cc8[u];
; #pragma unroll
;             for (int q = 0; q < 4; ++q) { const f8 t = __builtin_convertvector(*(const h8*)(p + q * SS), f8); v[u][2 * q] = (f32x4){t[0], t[1], t[2], t[3]}; v[u][2 * q + 1] = (f32x4){t[4], t[5], t[6], t[7]}; }
;         }
; #pragma unroll
;         for (int u = 0; u < 2; ++u) {
;             if (!okk[u]) continue;
;             const f32x4 P0 = v[u][0] + v[u][2], P1 = v[u][1] + v[u][3], Q0 = v[u][4] + v[u][6], Q1 = v[u][5] + v[u][7];
;             *(u32x4*)(MIXo + (size_t)(bb[u] * SEQ + kk[u]) * KMO + 512 + cc8[u]) = gm::pack8(P0 + Q0, P1 + Q1);
;             if (kk[u] > 0) *(u32x4*)(MIXo + (size_t)(bb[u] * SEQ + SEQ - kk[u]) * KMO + 512 + cc8[u]) = gm::pack8(P0 - Q0, P1 - Q1);
;         }
.LBB0_133:
	v_add_u32_e32 v39, s1, v0
	s_mov_b32 s5, 0x80000
	v_cmp_gt_i32_e64 s[34:35], s5, v39
	v_ashrrev_i32_e32 v20, 9, v0
	v_readlane_b32 s12, v252, 6
	v_cndmask_b32_e64 v6, v0, v39, s[34:35]
	v_ashrrev_i32_e32 v16, 9, v6
	v_ashrrev_i32_e32 v17, 31, v16
	v_bfe_u32 v40, v6, 6, 3
	v_lshlrev_b64 v[2:3], 13, v[16:17]
	v_readlane_b32 s13, v252, 7
	v_ashrrev_i32_e32 v21, 31, v20
	v_lshlrev_b32_e32 v80, 10, v40
	v_lshl_add_u64 v[2:3], s[12:13], 0, v[2:3]
	v_lshlrev_b64 v[4:5], 13, v[20:21]
	v_bfe_u32 v17, v0, 6, 3
	v_lshl_add_u64 v[2:3], v[2:3], 0, v[80:81]
	v_lshl_add_u64 v[4:5], s[12:13], 0, v[4:5]
	v_lshlrev_b32_e32 v80, 10, v17
	v_lshl_add_u64 v[0:1], v[4:5], 0, v[80:81]
	v_and_b32_e32 v4, 0x1f8, v38
	v_lshlrev_b32_e32 v80, 1, v4
	v_lshl_add_u64 v[0:1], v[0:1], 0, v[80:81]
	s_mov_b32 s12, 0x1800000
	v_add_co_u32_e32 v4, vcc, s12, v0
	s_mov_b32 s9, 0x1000000
	s_nop 0
	v_addc_co_u32_e32 v5, vcc, 0, v1, vcc
	global_load_dwordx4 v[22:25], v[4:5], off
	v_add_co_u32_e32 v4, vcc, s9, v0
	s_mov_b32 s5, 0x800000
	s_nop 0
	v_addc_co_u32_e32 v5, vcc, 0, v1, vcc
	global_load_dwordx4 v[26:29], v[4:5], off
	v_add_co_u32_e32 v4, vcc, s5, v0
	v_mov_b32_e32 v19, v81
	s_nop 0
	v_addc_co_u32_e32 v5, vcc, 0, v1, vcc
	global_load_dwordx4 v[30:33], v[4:5], off
	global_load_dwordx4 v[34:37], v[0:1], off
	v_lshlrev_b32_e32 v0, 3, v6
	v_and_b32_e32 v0, 0x1f8, v0
	v_lshlrev_b32_e32 v18, 1, v0
	v_lshl_add_u64 v[0:1], v[2:3], 0, v[18:19]
	v_add_co_u32_e32 v2, vcc, s5, v0
	v_lshlrev_b32_e32 v17, 11, v17
	s_nop 0
	v_addc_co_u32_e32 v3, vcc, 0, v1, vcc
	v_add_co_u32_e32 v4, vcc, s9, v0
	s_nop 0
	v_addc_co_u32_e32 v5, vcc, 0, v1, vcc
	v_add_co_u32_e32 v42, vcc, s12, v0
	s_nop 0
	s_nop 0
	v_addc_co_u32_e32 v43, vcc, 0, v1, vcc
	global_load_dwordx4 v[12:15], v[0:1], off
	global_load_dwordx4 v[8:11], v[2:3], off
	s_nop 0
	global_load_dwordx4 v[4:7], v[4:5], off
	s_nop 0
	global_load_dwordx4 v[0:3], v[42:43], off
	s_waitcnt vmcnt(7)
	v_cvt_f32_f16_e32 v44, v23
	v_cvt_f32_f16_sdwa v45, v23 dst_sel:DWORD dst_unused:UNUSED_PAD src0_sel:WORD_1
	v_cvt_f32_f16_e32 v42, v22
	v_cvt_f32_f16_sdwa v43, v22 dst_sel:DWORD dst_unused:UNUSED_PAD src0_sel:WORD_1
	v_cvt_f32_f16_e32 v46, v24
	v_cvt_f32_f16_sdwa v47, v24 dst_sel:DWORD dst_unused:UNUSED_PAD src0_sel:WORD_1
	v_cvt_f32_f16_e32 v48, v25
	v_cvt_f32_f16_sdwa v49, v25 dst_sel:DWORD dst_unused:UNUSED_PAD src0_sel:WORD_1
	s_waitcnt vmcnt(6)
	v_cvt_f32_f16_e32 v50, v26
	v_cvt_f32_f16_sdwa v51, v26 dst_sel:DWORD dst_unused:UNUSED_PAD src0_sel:WORD_1
	v_cvt_f32_f16_e32 v52, v27
	v_cvt_f32_f16_sdwa v53, v27 dst_sel:DWORD dst_unused:UNUSED_PAD src0_sel:WORD_1
	v_cvt_f32_f16_e32 v54, v28
	v_cvt_f32_f16_sdwa v55, v28 dst_sel:DWORD dst_unused:UNUSED_PAD src0_sel:WORD_1
	v_cvt_f32_f16_e32 v56, v29
	v_cvt_f32_f16_sdwa v57, v29 dst_sel:DWORD dst_unused:UNUSED_PAD src0_sel:WORD_1
	s_waitcnt vmcnt(5)
	v_cvt_f32_f16_e32 v28, v30
	v_cvt_f32_f16_sdwa v29, v30 dst_sel:DWORD dst_unused:UNUSED_PAD src0_sel:WORD_1
	v_cvt_f32_f16_e32 v26, v31
	v_cvt_f32_f16_sdwa v27, v31 dst_sel:DWORD dst_unused:UNUSED_PAD src0_sel:WORD_1
	v_cvt_f32_f16_e32 v24, v32
	v_cvt_f32_f16_sdwa v25, v32 dst_sel:DWORD dst_unused:UNUSED_PAD src0_sel:WORD_1
	v_cvt_f32_f16_e32 v22, v33
	v_cvt_f32_f16_sdwa v23, v33 dst_sel:DWORD dst_unused:UNUSED_PAD src0_sel:WORD_1
	s_waitcnt vmcnt(4)
	v_cvt_f32_f16_e32 v30, v34
	v_cvt_f32_f16_e32 v32, v35
	v_cvt_f32_f16_e32 v60, v37
	v_cvt_f32_f16_sdwa v61, v37 dst_sel:DWORD dst_unused:UNUSED_PAD src0_sel:WORD_1
	v_cvt_f32_f16_sdwa v33, v35 dst_sel:DWORD dst_unused:UNUSED_PAD src0_sel:WORD_1
	v_cvt_f32_f16_sdwa v31, v34 dst_sel:DWORD dst_unused:UNUSED_PAD src0_sel:WORD_1
	v_cvt_f32_f16_e32 v58, v36
	v_cvt_f32_f16_sdwa v59, v36 dst_sel:DWORD dst_unused:UNUSED_PAD src0_sel:WORD_1
	v_pk_add_f32 v[22:23], v[22:23], v[60:61]
	v_pk_add_f32 v[26:27], v[26:27], v[32:33]
	v_pk_add_f32 v[28:29], v[28:29], v[30:31]
	v_pk_add_f32 v[30:31], v[48:49], v[56:57]
	v_pk_add_f32 v[34:35], v[44:45], v[52:53]
	v_pk_add_f32 v[36:37], v[42:43], v[50:51]
	v_pk_add_f32 v[32:33], v[46:47], v[54:55]
	v_pk_add_f32 v[44:45], v[34:35], v[26:27]
	v_pk_add_f32 v[42:43], v[36:37], v[28:29]
	v_pk_add_f32 v[46:47], v[30:31], v[22:23]
	v_cvt_pk_bf16_f32 v42, v42, v43
	v_cvt_pk_bf16_f32 v43, v44, v45
	v_cvt_pk_bf16_f32 v45, v46, v47
	v_add_u32_e32 v46, v17, v20
	v_ashrrev_i32_e32 v47, 31, v46
	v_readlane_b32 s12, v252, 4
	v_pk_add_f32 v[24:25], v[24:25], v[58:59]
	v_lshlrev_b64 v[46:47], 11, v[46:47]
	v_readlane_b32 s13, v252, 5
	v_pk_add_f32 v[48:49], v[32:33], v[24:25]
	v_cmp_lt_i32_e32 vcc, 0, v20
	v_lshl_add_u64 v[46:47], s[12:13], 0, v[46:47]
	v_cvt_pk_bf16_f32 v44, v48, v49
	v_lshl_add_u64 v[46:47], v[46:47], 0, v[80:81]
	global_store_dwordx4 v[46:47], v[42:45], off offset:1024 sc1
	s_and_saveexec_b64 s[12:13], vcc
	s_cbranch_execz .LBB0_135
	v_sub_u32_e32 v17, v17, v20
	v_sub_f32_e32 v19, v27, v35
	v_sub_f32_e32 v21, v26, v34
	v_lshlrev_b32_e32 v20, 11, v17
	v_readlane_b32 s16, v252, 4
	v_sub_f32_e32 v27, v28, v36
	v_sub_f32_e32 v28, v23, v31
	v_cvt_pk_bf16_f32 v23, v21, v19
	v_ashrrev_i32_e32 v21, 31, v20
	v_readlane_b32 s17, v252, 5
	v_sub_f32_e32 v26, v29, v37
	v_sub_f32_e32 v29, v22, v30
	v_lshl_add_u64 v[20:21], s[16:17], 0, v[20:21]
	v_lshl_add_u64 v[20:21], v[20:21], 0, v[80:81]
	v_sub_f32_e32 v25, v25, v33
	v_sub_f32_e32 v24, v24, v32
	v_add_co_u32_e32 v20, vcc, 0x400000, v20
	v_cvt_pk_bf16_f32 v22, v27, v26
	v_cvt_pk_bf16_f32 v24, v24, v25
	v_cvt_pk_bf16_f32 v25, v29, v28
	v_addc_co_u32_e32 v21, vcc, 0, v21, vcc
	global_store_dwordx4 v[20:21], v[22:25], off offset:1024 sc1
; __device__ __forceinline__ u32x4 pack8(const f32x4& a, const f32x4& b) { u32x4 w; w.x = cvt_pk_bf16(a[0], a[1]); w.y = cvt_pk_bf16(a[2], a[3]); w.z = cvt_pk_bf16(b[0], b[1]); w.w = cvt_pk_bf16(b[2], b[3]); return w; }
; __device__ __forceinline__ void dft_combine(const Args& a, int gt, int NT, int lane, int gw, int NGW) {
;     ...
; #pragma unroll
;         for (int u = 0; u < 2; ++u) {
;             if (!okk[u]) continue;
;             const f32x4 P0 = v[u][0] + v[u][2], P1 = v[u][1] + v[u][3], Q0 = v[u][4] + v[u][6], Q1 = v[u][5] + v[u][7];
;             *(u32x4*)(MIXo + (size_t)(bb[u] * SEQ + kk[u]) * KMO + 512 + cc8[u]) = gm::pack8(P0 + Q0, P1 + Q1);
;             if (kk[u] > 0) *(u32x4*)(MIXo + (size_t)(bb[u] * SEQ + SEQ - kk[u]) * KMO + 512 + cc8[u]) = gm::pack8(P0 - Q0, P1 - Q1);
;         }
.LBB0_135:
	s_or_b64 exec, exec, s[12:13]
	s_and_saveexec_b64 s[40:41], s[34:35]
	s_mov_b32 s5, 0x7ffff
	s_cbranch_execz .LBB0_132
	s_waitcnt vmcnt(4)
	v_cvt_f32_f16_sdwa v21, v12 dst_sel:DWORD dst_unused:UNUSED_PAD src0_sel:WORD_1
	v_cvt_f32_f16_sdwa v23, v13 dst_sel:DWORD dst_unused:UNUSED_PAD src0_sel:WORD_1
	v_cvt_f32_f16_sdwa v25, v14 dst_sel:DWORD dst_unused:UNUSED_PAD src0_sel:WORD_1
	v_cvt_f32_f16_sdwa v27, v15 dst_sel:DWORD dst_unused:UNUSED_PAD src0_sel:WORD_1
	v_cvt_f32_f16_e32 v20, v12
	v_cvt_f32_f16_e32 v22, v13
	v_cvt_f32_f16_e32 v24, v14
	v_cvt_f32_f16_e32 v26, v15
	s_waitcnt vmcnt(3)
	v_cvt_f32_f16_sdwa v13, v8 dst_sel:DWORD dst_unused:UNUSED_PAD src0_sel:WORD_1
	v_cvt_f32_f16_sdwa v15, v9 dst_sel:DWORD dst_unused:UNUSED_PAD src0_sel:WORD_1
	v_cvt_f32_f16_sdwa v31, v11 dst_sel:DWORD dst_unused:UNUSED_PAD src0_sel:WORD_1
	v_cvt_f32_f16_e32 v12, v8
	v_cvt_f32_f16_e32 v14, v9
	v_cvt_f32_f16_e32 v30, v11
	s_waitcnt vmcnt(2)
	v_cvt_f32_f16_sdwa v33, v4 dst_sel:DWORD dst_unused:UNUSED_PAD src0_sel:WORD_1
	v_cvt_f32_f16_sdwa v35, v5 dst_sel:DWORD dst_unused:UNUSED_PAD src0_sel:WORD_1
	v_cvt_f32_f16_sdwa v9, v7 dst_sel:DWORD dst_unused:UNUSED_PAD src0_sel:WORD_1
	v_cvt_f32_f16_e32 v32, v4
	v_cvt_f32_f16_e32 v34, v5
	v_cvt_f32_f16_e32 v8, v7
	s_waitcnt vmcnt(1)
	v_cvt_f32_f16_sdwa v37, v0 dst_sel:DWORD dst_unused:UNUSED_PAD src0_sel:WORD_1
	v_cvt_f32_f16_sdwa v43, v1 dst_sel:DWORD dst_unused:UNUSED_PAD src0_sel:WORD_1
	v_cvt_f32_f16_sdwa v47, v3 dst_sel:DWORD dst_unused:UNUSED_PAD src0_sel:WORD_1
	v_cvt_f32_f16_e32 v36, v0
	v_cvt_f32_f16_e32 v42, v1
	v_cvt_f32_f16_e32 v46, v3
	v_cvt_f32_f16_sdwa v29, v10 dst_sel:DWORD dst_unused:UNUSED_PAD src0_sel:WORD_1
	v_cvt_f32_f16_e32 v28, v10
	v_cvt_f32_f16_sdwa v11, v6 dst_sel:DWORD dst_unused:UNUSED_PAD src0_sel:WORD_1
	v_cvt_f32_f16_e32 v10, v6
	v_cvt_f32_f16_sdwa v45, v2 dst_sel:DWORD dst_unused:UNUSED_PAD src0_sel:WORD_1
	v_cvt_f32_f16_e32 v44, v2
	v_pk_add_f32 v[0:1], v[26:27], v[30:31]
	v_pk_add_f32 v[4:5], v[22:23], v[14:15]
	v_pk_add_f32 v[6:7], v[20:21], v[12:13]
	v_pk_add_f32 v[8:9], v[8:9], v[46:47]
	v_pk_add_f32 v[12:13], v[34:35], v[42:43]
	v_pk_add_f32 v[14:15], v[32:33], v[36:37]
	v_pk_add_f32 v[2:3], v[24:25], v[28:29]
	v_pk_add_f32 v[22:23], v[4:5], v[12:13]
	v_pk_add_f32 v[20:21], v[6:7], v[14:15]
	v_pk_add_f32 v[24:25], v[0:1], v[8:9]
	v_lshlrev_b32_e32 v17, 11, v40
	v_cvt_pk_bf16_f32 v20, v20, v21
	v_cvt_pk_bf16_f32 v21, v22, v23
	v_cvt_pk_bf16_f32 v23, v24, v25
	v_add_u32_e32 v24, v17, v16
	v_ashrrev_i32_e32 v25, 31, v24
	v_readlane_b32 s12, v252, 4
	v_pk_add_f32 v[10:11], v[10:11], v[44:45]
	v_lshlrev_b64 v[24:25], 11, v[24:25]
	v_readlane_b32 s13, v252, 5
	v_pk_add_f32 v[26:27], v[2:3], v[10:11]
	v_mov_b32_e32 v19, v81
	v_lshl_add_u64 v[24:25], s[12:13], 0, v[24:25]
	v_cvt_pk_bf16_f32 v22, v26, v27
	v_lshl_add_u64 v[24:25], v[24:25], 0, v[18:19]
	v_cmp_lt_i32_e32 vcc, 0, v16
	global_store_dwordx4 v[24:25], v[20:23], off offset:1024 sc1
	s_and_b64 exec, exec, vcc
	s_cbranch_execz .LBB0_132
	v_sub_f32_e32 v5, v5, v13
	v_sub_f32_e32 v4, v4, v12
	v_sub_f32_e32 v9, v1, v9
	v_cvt_pk_bf16_f32 v1, v4, v5
	v_sub_u32_e32 v4, v17, v16
	v_ashrrev_i32_e32 v5, 31, v4
	v_readlane_b32 s12, v252, 4
	v_lshlrev_b64 v[4:5], 11, v[4:5]
	v_readlane_b32 s13, v252, 5
	v_sub_f32_e32 v7, v7, v15
	v_sub_f32_e32 v6, v6, v14
	v_lshl_add_u64 v[4:5], s[12:13], 0, v[4:5]
	v_lshl_add_u64 v[4:5], v[4:5], 0, v[18:19]
	v_sub_f32_e32 v8, v0, v8
	v_sub_f32_e32 v3, v3, v11
	v_sub_f32_e32 v2, v2, v10
	v_add_co_u32_e32 v4, vcc, 0x400000, v4
	v_cvt_pk_bf16_f32 v0, v6, v7
	v_cvt_pk_bf16_f32 v2, v2, v3
	v_cvt_pk_bf16_f32 v3, v8, v9
	v_addc_co_u32_e32 v5, vcc, 0, v5, vcc
	global_store_dwordx4 v[4:5], v[0:3], off offset:1024 sc1
	s_branch .LBB0_132
	s_nop 0
	s_nop 0
	s_nop 0
	s_nop 0
	s_nop 0
	s_nop 0
	s_nop 0
	s_nop 0
	s_nop 0
	s_nop 0
	s_nop 0
	s_nop 0
	s_nop 0
	s_nop 0
